# diff LDS-DMA issue: M0 written directly by the SALU add (one SALU instruction fewer per load)
# speedup vs baseline: 1.0077x; 1.0041x over previous
; #define LAS __attribute__((address_space(3)))
; #define MFMA(a, b, c) __builtin_amdgcn_mfma_f32_32x32x16_bf16((a), (b), (c), 0, 0, 0)
; template <typename F>
; DI void diff_step(lptr sK, lptr sV, int kx0, int vl0, const bf16x8 (&qf)[4], float& m, float& l, f32x16 (&O)[4],
;                   const LAS float* tb, bool far, float cfar, int lane, F&& mid) {
;     ...
;     for (int s = 0; s < 4; ++s) {
;         const int co = (kx0 ^ (2 * s)) * 16;
;         kf[2 * s] = *(const LAS bf16x8*)(kr + co);
;         kf[2 * s + 1] = *(const LAS bf16x8*)(kr + 8192 + co);
;     }
;     __builtin_amdgcn_sched_barrier(0);
;     mid();
;     __builtin_amdgcn_sched_barrier(0);
; #pragma unroll
;     for (int s = 0; s < 4; ++s) { p0 = MFMA(kf[2 * s], qf[s], p0); p1 = MFMA(kf[2 * s + 1], qf[s], p1); }
.Ldu_A:
	s_waitcnt vmcnt(0)
	s_waitcnt lgkmcnt(0)
	s_barrier
	ds_read_b128 v[80:83], v14
	ds_read_b128 v[120:123], v15
	ds_read_b128 v[116:119], v221
	ds_read_b128 v[10:13], v222
	ds_read_b128 v[84:87], v14 offset:8192
	ds_read_b128 v[6:9], v15 offset:8192
	ds_read_b128 v[2:5], v221 offset:8192
	ds_read_b128 v[112:115], v222 offset:8192
	v_add_u32_e32 v220, 1, v220
	s_add_u32 m0, s63, 0x8000
	s_nop 0
	global_load_lds_dwordx4 v170, s[64:65]
	s_add_u32 m0, s63, 0xc000
	s_nop 0
	global_load_lds_dwordx4 v170, s[70:71]
	s_add_u32 m0, s63, 0x8400
	s_nop 0
	global_load_lds_dwordx4 v172, s[64:65]
	s_add_u32 m0, s63, 0xc400
	s_nop 0
	global_load_lds_dwordx4 v172, s[70:71]
	s_add_u32 s64, s64, 0xe0000
	s_addc_u32 s65, s65, 0
	s_add_u32 s70, s70, 0xe0000
	s_addc_u32 s71, s71, 0
	v_cmp_gt_i32_e32 vcc, s42, v217
	s_waitcnt lgkmcnt(7)
	v_mfma_f32_32x32x16_bf16 v[96:111], v[80:83], v[144:147], 0
	s_waitcnt lgkmcnt(6)
	v_mfma_f32_32x32x16_bf16 v[96:111], v[120:123], v[148:151], v[96:111]
	s_waitcnt lgkmcnt(5)
	v_mfma_f32_32x32x16_bf16 v[96:111], v[116:119], v[152:155], v[96:111]
	s_waitcnt lgkmcnt(4)
	v_mfma_f32_32x32x16_bf16 v[96:111], v[10:13], v[156:159], v[96:111]
	ds_read_b64_tr_b16 v[10:11], v213 offset:16384
	ds_read_b64_tr_b16 v[12:13], v214 offset:18432
	ds_read_b64_tr_b16 v[160:161], v215 offset:16384
	ds_read_b64_tr_b16 v[162:163], v216 offset:18432
	s_waitcnt lgkmcnt(7)
	v_mfma_f32_32x32x16_bf16 v[80:95], v[84:87], v[144:147], 0
	s_waitcnt lgkmcnt(6)
	v_mfma_f32_32x32x16_bf16 v[80:95], v[6:9], v[148:151], v[80:95]
	ds_read_b64_tr_b16 v[6:7], v211 offset:16384
	ds_read_b64_tr_b16 v[8:9], v212 offset:18432
	s_waitcnt lgkmcnt(7)
	v_mfma_f32_32x32x16_bf16 v[80:95], v[2:5], v[152:155], v[80:95]
	ds_read_b64_tr_b16 v[2:3], v199 offset:16384
	ds_read_b64_tr_b16 v[4:5], v210 offset:18432
	s_waitcnt lgkmcnt(8)
	v_mfma_f32_32x32x16_bf16 v[80:95], v[112:115], v[156:159], v[80:95]
	s_and_saveexec_b64 s[22:23], vcc
	s_xor_b64 s[22:23], exec, s[22:23]
	s_cbranch_execz .LBB0_258_a
	ds_read2_b32 v[112:113], v218 offset0:58 offset1:59
	ds_read2_b32 v[114:115], v218 offset0:56 offset1:57
	ds_read2_b32 v[116:117], v218 offset0:50 offset1:51
	ds_read2_b32 v[118:119], v218 offset0:48 offset1:49
	ds_read2_b32 v[128:129], v218 offset0:42 offset1:43
	ds_read2_b32 v[130:131], v218 offset0:40 offset1:41
	ds_read2_b32 v[132:133], v218 offset0:34 offset1:35
	ds_read2_b32 v[134:135], v218 offset0:32 offset1:33
	ds_read2_b32 v[120:121], v218 offset0:26 offset1:27
	ds_read2_b32 v[122:123], v218 offset0:24 offset1:25
	ds_read2_b32 v[124:125], v218 offset0:18 offset1:19
	ds_read2_b32 v[126:127], v218 offset0:16 offset1:17
	ds_read2_b32 v[136:137], v218 offset0:10 offset1:11
	ds_read2_b32 v[138:139], v218 offset0:8 offset1:9
	ds_read2_b32 v[140:141], v218 offset0:2 offset1:3
	ds_read2_b32 v[142:143], v218 offset1:1
	s_waitcnt lgkmcnt(8)
	v_fmamk_f32 v96, v96, 0x3e38aa3b, v113
	v_fmamk_f32 v97, v97, 0x3e38aa3b, v112
	v_fmamk_f32 v98, v98, 0x3e38aa3b, v115
	v_fmamk_f32 v99, v99, 0x3e38aa3b, v114
	v_fmamk_f32 v100, v100, 0x3e38aa3b, v117
	v_fmamk_f32 v101, v101, 0x3e38aa3b, v116
	v_fmamk_f32 v102, v102, 0x3e38aa3b, v119
	v_fmamk_f32 v103, v103, 0x3e38aa3b, v118
	v_fmamk_f32 v104, v104, 0x3e38aa3b, v129
	v_fmamk_f32 v105, v105, 0x3e38aa3b, v128
	v_fmamk_f32 v106, v106, 0x3e38aa3b, v131
	v_fmamk_f32 v107, v107, 0x3e38aa3b, v130
	v_fmamk_f32 v108, v108, 0x3e38aa3b, v133
	v_fmamk_f32 v109, v109, 0x3e38aa3b, v132
	v_fmamk_f32 v110, v110, 0x3e38aa3b, v135
	v_fmamk_f32 v111, v111, 0x3e38aa3b, v134
	v_max3_f32 v112, v96, v97, v98
	v_max3_f32 v113, v99, v100, v101
	v_max3_f32 v112, v112, v102, v103
	v_max3_f32 v113, v113, v104, v105
	v_max3_f32 v112, v112, v106, v107
	v_max3_f32 v113, v113, v108, v109
	v_max3_f32 v112, v112, v110, v111
	s_waitcnt lgkmcnt(0)
	v_fmamk_f32 v80, v80, 0x3e38aa3b, v121
	v_fmamk_f32 v81, v81, 0x3e38aa3b, v120
	v_fmamk_f32 v82, v82, 0x3e38aa3b, v123
	v_fmamk_f32 v83, v83, 0x3e38aa3b, v122
	v_fmamk_f32 v84, v84, 0x3e38aa3b, v125
	v_fmamk_f32 v85, v85, 0x3e38aa3b, v124
	v_fmamk_f32 v86, v86, 0x3e38aa3b, v127
	v_fmamk_f32 v87, v87, 0x3e38aa3b, v126
	v_fmamk_f32 v88, v88, 0x3e38aa3b, v137
	v_fmamk_f32 v89, v89, 0x3e38aa3b, v136
	v_fmamk_f32 v90, v90, 0x3e38aa3b, v139
	v_fmamk_f32 v91, v91, 0x3e38aa3b, v138
	v_fmamk_f32 v92, v92, 0x3e38aa3b, v141
	v_fmamk_f32 v93, v93, 0x3e38aa3b, v140
	v_fmamk_f32 v94, v94, 0x3e38aa3b, v143
	v_fmamk_f32 v95, v95, 0x3e38aa3b, v142
	v_max3_f32 v112, v112, v80, v81
	v_max3_f32 v113, v113, v82, v83
	v_max3_f32 v112, v112, v84, v85
	v_max3_f32 v113, v113, v86, v87
	v_max3_f32 v112, v112, v88, v89
	v_max3_f32 v113, v113, v90, v91
	v_max3_f32 v112, v112, v92, v93
	v_max3_f32 v113, v113, v94, v95
	s_nop 0
	v_max_f32_e32 v113, v113, v113
	v_max_f32_e32 v112, v112, v112
	v_max_f32_e32 v112, v112, v113
	v_mov_b32_e32 v113, v112
	s_nop 1
	v_permlane32_swap_b32_e32 v112, v113
	v_max_f32_e32 v113, v113, v113
	v_max_f32_e32 v112, v112, v112
	v_max_f32_e32 v112, v112, v113
	v_sub_f32_e32 v113, v112, v226
	v_cmp_lt_f32_e32 vcc, s45, v113
	v_max_f32_e32 v112, v226, v112
	s_nop 0
	v_cndmask_b32_e32 v227, v226, v112, vcc
	v_sub_f32 v112, v96, v227
	v_sub_f32 v128, v80, v227
	v_sub_f32 v113, v97, v227
	v_sub_f32 v129, v81, v227
	v_sub_f32 v114, v98, v227
	v_sub_f32 v130, v82, v227
	v_sub_f32 v115, v99, v227
	v_sub_f32 v131, v83, v227
	v_sub_f32 v116, v100, v227
	v_sub_f32 v132, v84, v227
	v_sub_f32 v117, v101, v227
	v_sub_f32 v133, v85, v227
	v_sub_f32 v118, v102, v227
	v_sub_f32 v134, v86, v227
	v_sub_f32 v119, v103, v227
	v_sub_f32 v135, v87, v227
	v_sub_f32 v120, v104, v227
	v_sub_f32 v136, v88, v227
	v_sub_f32 v121, v105, v227
	v_sub_f32 v137, v89, v227
	v_sub_f32 v122, v106, v227
	v_sub_f32 v138, v90, v227
	v_sub_f32 v123, v107, v227
	v_sub_f32 v139, v91, v227
	v_sub_f32 v124, v108, v227
	v_sub_f32 v140, v92, v227
	v_sub_f32 v125, v109, v227
	v_sub_f32 v141, v93, v227
	v_sub_f32 v126, v110, v227
	v_sub_f32 v142, v94, v227
	v_sub_f32 v127, v111, v227
	v_sub_f32 v143, v95, v227

; #define LAS __attribute__((address_space(3)))
; DI void diff_item(const Params& P, char* lds, int layer, int pair, int qt, int& tab_head) {
;     ...
;     auto issue = [&](int kt, int buf) {
;         const size_t to = (size_t)(64 * kt) * PO;
; #pragma unroll
;         for (int i = 0; i < 2; ++i) {
;             glds16(kg + to + goff[i], (unsigned)__builtin_amdgcn_readfirstlane(lds0 + buf * 32768 + (2 * w + i) * 1024));
;             glds16(vg + to + goff[i], (unsigned)__builtin_amdgcn_readfirstlane(lds0 + buf * 32768 + 16384 + (2 * w + i) * 1024));
;         }
;     };
;     ...
;     for (int kt = 0; kt < nkt; ++kt) {
;         asm volatile("s_waitcnt vmcnt(0)" ::: "memory");
;         __syncthreads();
;         auto mid = [&]() { if (kt + 1 < nkt) issue(kt + 1, (kt + 1) & 1); };
;         if (64 * kt <= q0 + 32 * qs + 31) {
;             const bool far = (q0 + 32 * qs) - (64 * kt + 63) >= 1536;
;             const LAS float* tb = (const LAS float*)ctab + (qpos - 64 * kt - 4 * hh + 64 - 63);
.Ldu_B:
	s_waitcnt vmcnt(0)
	s_sub_i32 s22, s50, 64
	v_cmp_le_u32_e32 vcc, s22, v200
	v_add_u32_e32 v0, 1, v220
	s_waitcnt lgkmcnt(0)
	s_barrier
	s_and_saveexec_b64 s[22:23], vcc
	s_xor_b64 s[40:41], exec, s[22:23]
	s_cbranch_execz .LBB0_263_b
	v_add_u32_e32 v220, 1, v220
	v_cmp_gt_u32_e32 vcc, s49, v220
	ds_read_b128 v[80:83], v14 offset:32768
	ds_read_b128 v[120:123], v15 offset:32768
	ds_read_b128 v[116:119], v221 offset:32768
	ds_read_b128 v[10:13], v222 offset:32768
	ds_read_b128 v[84:87], v14 offset:40960
	ds_read_b128 v[6:9], v15 offset:40960
	ds_read_b128 v[2:5], v221 offset:40960
	ds_read_b128 v[112:115], v222 offset:40960
	s_and_saveexec_b64 s[22:23], vcc
	s_cbranch_execz .LBB0_256_b
	s_mov_b32 m0, s63
	s_nop 0
	global_load_lds_dwordx4 v170, s[64:65]
	s_add_u32 m0, s63, 0x4000
	s_nop 0
	global_load_lds_dwordx4 v170, s[70:71]
	s_add_u32 m0, s63, 0x400
	s_nop 0
	global_load_lds_dwordx4 v172, s[64:65]
	s_add_u32 m0, s63, 0x4400
	s_nop 0
	global_load_lds_dwordx4 v172, s[70:71]
	s_add_u32 s64, s64, 0xe0000
	s_addc_u32 s65, s65, 0
	s_add_u32 s70, s70, 0xe0000
	s_addc_u32 s71, s71, 0

; #define LAS __attribute__((address_space(3)))
; DI void diff_item(const Params& P, char* lds, int layer, int pair, int qt, int& tab_head) {
;     ...
;     auto issue = [&](int kt, int buf) {
;         const size_t to = (size_t)(64 * kt) * PO;
; #pragma unroll
;         for (int i = 0; i < 2; ++i) {
;             glds16(kg + to + goff[i], (unsigned)__builtin_amdgcn_readfirstlane(lds0 + buf * 32768 + (2 * w + i) * 1024));
;             glds16(vg + to + goff[i], (unsigned)__builtin_amdgcn_readfirstlane(lds0 + buf * 32768 + 16384 + (2 * w + i) * 1024));
;         }
;     };
;     ...
;         auto mid = [&]() { if (kt + 1 < nkt) issue(kt + 1, (kt + 1) & 1); };
;         if (64 * kt <= q0 + 32 * qs + 31) {
;             const bool far = (q0 + 32 * qs) - (64 * kt + 63) >= 1536;
;             const LAS float* tb = (const LAS float*)ctab + (qpos - 64 * kt - 4 * hh + 64 - 63);
;             lptr bufp = (lptr)lds + (kt & 1) * 32768;
;             diff_step(bufp, bufp + 16384, kx0, vl0, qf, m, l, O, tb, far, cfar, lane, mid);
;         } else mid();
.LBB0_263_b:
	s_andn2_saveexec_b64 s[22:23], s[40:41]
	s_cbranch_execz .LBB0_252_b
	v_cmp_gt_u32_e32 vcc, s49, v0
	s_and_saveexec_b64 s[40:41], vcc
	s_cbranch_execz .LBB0_251_b
	s_mov_b32 m0, s63
	s_nop 0
	global_load_lds_dwordx4 v170, s[64:65]
	s_add_u32 m0, s63, 0x4000
	s_nop 0
	global_load_lds_dwordx4 v170, s[70:71]
	s_add_u32 m0, s63, 0x400
	s_nop 0
	global_load_lds_dwordx4 v172, s[64:65]
	s_add_u32 m0, s63, 0x4400
	s_nop 0
	global_load_lds_dwordx4 v172, s[70:71]
	s_add_u32 s64, s64, 0xe0000
	s_addc_u32 s65, s65, 0
	s_add_u32 s70, s70, 0xe0000
	s_addc_u32 s71, s71, 0
	s_branch .LBB0_251_b
